# MIXA attention loop: 16 per-chunk exec-mask bias guards replaced by one scalar SCC test with out-of-line near blocks
# speedup vs baseline: 1.0107x; 1.0107x over previous
; DI unsigned pk2(float a, float b) { f32x2 v = {a, b}; return __builtin_bit_cast(unsigned, __builtin_convertvector(v, bf16x2)); }
; template <int DQK, bool MIXA, bool PIPE>
; DI void attn_item(const Params& P, int layer, char* smem, int b, int h, int qt) {
;     ...
;         f32x2 p2 = {__builtin_amdgcn_exp2f(xv2.x), __builtin_amdgcn_exp2f(xv2.y)};
;         if (MIXA) {
;           float px = p2.x, py = p2.y;
;           asm volatile("v_add_co_u32 %0, vcc, %0, %0\n\tv_cndmask_b32 %1, 0, %1, vcc" : "+v"(mrot[kb]), "+v"(py) : : "vcc");
;           asm volatile("v_add_co_u32 %0, vcc, %0, %0\n\tv_cndmask_b32 %1, 0, %1, vcc" : "+v"(mrot[kb]), "+v"(px) : : "vcc");
;           p2.x = px; p2.y = py;
;         }
;         ls2 += p2;
;         pkw[kb][s2][e] = pk2(p2.x, p2.y);
;       };
;       {
;         int c0 = 0;
; #pragma unroll
;         for (int s = 0; s < NS; ++s) {
;           sacc[1] = __builtin_amdgcn_mfma_f32_32x32x16_bf16(kf[1][s], qf[s], sacc[1], 0, 0, 0);
;           const int cend = (8 * (s + 1)) / NS;
; #pragma unroll
;           for (int c = 0; c < 8; ++c) if (c >= c0 && c < cend) chunk(0, c);
;           c0 = cend;
;           __builtin_amdgcn_sched_barrier(0);
;         }
;       }
;       bf16x8 pf0[2], pf1[2];
; #pragma unroll
;       for (int s2 = 0; s2 < 2; ++s2) { u32x4 t = {pkw[0][s2][0], pkw[0][s2][1], pkw[0][s2][2], pkw[0][s2][3]}; pf0[s2] = __builtin_bit_cast(bf16x8, t); }
; #pragma unroll
;       for (int j = 0; j < 4; ++j) {
;         const int s2 = j >> 1, d = j & 1;
;         o[d] = __builtin_amdgcn_mfma_f32_32x32x16_bf16(vf[d][0][s2], pf0[s2], o[d], 0, 0, 0);
;         chunk(1, 2 * j); chunk(1, 2 * j + 1);
;         __builtin_amdgcn_sched_barrier(0);
;       }
; #pragma unroll
;       for (int s2 = 0; s2 < 2; ++s2) { u32x4 t = {pkw[1][s2][0], pkw[1][s2][1], pkw[1][s2][2], pkw[1][s2][3]}; pf1[s2] = __builtin_bit_cast(bf16x8, t); }
; #pragma unroll
;       for (int j = 0; j < 4; ++j) {
;         const int s2 = j >> 1, d = j & 1;
;         o[d] = __builtin_amdgcn_mfma_f32_32x32x16_bf16(vf[d][1][s2], pf1[s2], o[d], 0, 0, 0);
;       }
;       l += ls2.x + ls2.y;
.LBB0_108:
	v_pk_add_f32 v[40:41], v[62:63], 0 op_sel_hi:[1,0]
	v_exp_f32_e32 v33, v33
	v_pk_add_f32 v[40:41], v[40:41], v[60:61]
	v_exp_f32_e32 v32, v32
	v_pk_add_f32 v[40:41], v[40:41], v[58:59]
	v_add_co_u32 v100, vcc, v100, v100
	v_cndmask_b32 v33, 0, v33, vcc
	s_nop 0
	v_pk_add_f32 v[40:41], v[40:41], v[56:57]
	v_add_co_u32 v100, vcc, v100, v100
	v_cndmask_b32 v32, 0, v32, vcc
	s_nop 0
	v_pk_add_f32 v[40:41], v[40:41], v[54:55]
	s_nop 0
	v_pk_add_f32 v[40:41], v[40:41], v[52:53]
	s_nop 0
	v_pk_add_f32 v[40:41], v[40:41], v[116:117]
	s_nop 0
	v_pk_add_f32 v[40:41], v[40:41], v[118:119]
	s_nop 0
	v_pk_add_f32 v[40:41], v[40:41], v[46:47]
	s_nop 0
	v_pk_add_f32 v[40:41], v[40:41], v[44:45]
	s_nop 0
	v_pk_add_f32 v[40:41], v[40:41], v[48:49]
	s_nop 0
	v_pk_add_f32 v[40:41], v[40:41], v[50:51]
	s_nop 0
	v_pk_add_f32 v[40:41], v[40:41], v[38:39]
	s_nop 0
	v_pk_add_f32 v[40:41], v[40:41], v[36:37]
	v_cvt_pk_bf16_f32 v36, v36, v37
	v_pk_add_f32 v[42:43], v[40:41], v[34:35]
	v_cvt_pk_bf16_f32 v35, v34, v35
	v_cvt_pk_bf16_f32 v37, v38, v39
	v_cvt_pk_bf16_f32 v38, v50, v51
	v_cvt_pk_bf16_f32 v39, v48, v49
	v_cvt_pk_bf16_f32 v40, v44, v45
	v_cvt_pk_bf16_f32 v41, v46, v47
	v_cvt_pk_bf16_f32 v34, v32, v33
	s_nop 1
	v_mfma_f32_32x32x16_bf16 v[0:15], v[80:83], v[34:37], v[0:15]
	v_add_f32_e64 v32, v42, v32
	v_add_f32_e64 v33, v43, v33
	v_add_f32_e32 v32, v32, v33
	v_add_f32_e32 v125, v125, v32
	v_mfma_f32_32x32x16_bf16 v[16:31], v[92:95], v[34:37], v[16:31]
	v_mfma_f32_32x32x16_bf16 v[0:15], v[84:87], v[38:41], v[0:15]
	v_mfma_f32_32x32x16_bf16 v[16:31], v[88:91], v[38:41], v[16:31]

; template <int DQK, bool MIXA, bool PIPE>
; DI void attn_item(const Params& P, int layer, char* smem, int b, int h, int qt) {
;     ...
;     if (kt <= cw) {
;       const int kc = kt;
;       bf16x8 kf[2][NS];
; #pragma unroll
;       for (int kb = 0; kb < 2; ++kb)
; #pragma unroll
;         for (int s = 0; s < NS; ++s) kf[kb][s] = *(const bf16x8*)(Ks + (32 * kb + pr) * KROWB + (((2 * s + H) ^ swk) << 4));
;       __builtin_amdgcn_sched_barrier(0);
;       f32x16 sacc[2];
; #pragma unroll
;       for (int kb = 0; kb < 2; ++kb)
; #pragma unroll
;         for (int i = 0; i < 16; ++i) sacc[kb][i] = 0.f;
; #pragma unroll
;       for (int s = 0; s < NS; ++s) sacc[0] = __builtin_amdgcn_mfma_f32_32x32x16_bf16(kf[0][s], qf[s], sacc[0], 0, 0, 0);
;       bf16x8 vf[2][2][2];
; #pragma unroll
;       for (int d = 0; d < 2; ++d)
; #pragma unroll
;         for (int kb = 0; kb < 2; ++kb)
; #pragma unroll
;           for (int s2 = 0; s2 < 2; ++s2)
;             vf[d][kb][s2] = *(const bf16x8*)(Vs + (d * 32 + l31) * 128 + (((4 * kb + 2 * s2 + H) ^ swv) << 4));
;       __builtin_amdgcn_sched_barrier(0);
;       const bool near = MIXA && (kc >= cw - 2);
;       f32x2 ls2 = {0.f, 0.f};
;       const f32x2 sl2v = {sl2, sl2}, mfixv = {mfix, mfix};
;       unsigned pkw[2][2][4];
;       unsigned mrot[2];
; #pragma unroll
;       for (int kb = 0; kb < 2; ++kb) mrot[kb] = MIXA ? ((mw[kb] >> (8 * H)) << 8) : 0u;
;       auto chunk = [&](int kb, int c) __attribute__((always_inline)) {
;         const int s2 = 1 - (c >> 2), e = 3 - (c & 3);
;         const int r0 = 8 * s2 + 2 * e;
;         if (MIXA && c == 4) mrot[kb] <<= 8;
;         f32x2 xv2 = {sacc[kb][r0], sacc[kb][r0 + 1]};
;         xv2 = xv2 * sl2v - mfixv;
;         if (MIXA) {
;           if (near) {
;             const int kl = 16 * (r0 >> 3) + 8 * H + (r0 & 7);
;             const int rel = kc * 64 + 32 * kb + kl - qpos;
;             xv2.x += biasT[rel + 192];
;             xv2.y += biasT[rel + 193];
;           }
;         }
;         f32x2 p2 = {__builtin_amdgcn_exp2f(xv2.x), __builtin_amdgcn_exp2f(xv2.y)};
;         if (MIXA) {
;           float px = p2.x, py = p2.y;
;           asm volatile("v_add_co_u32 %0, vcc, %0, %0\n\tv_cndmask_b32 %1, 0, %1, vcc" : "+v"(mrot[kb]), "+v"(py) : : "vcc");
;           asm volatile("v_add_co_u32 %0, vcc, %0, %0\n\tv_cndmask_b32 %1, 0, %1, vcc" : "+v"(mrot[kb]), "+v"(px) : : "vcc");
.LBB0_112:
	s_or_b64 exec, exec, s[18:19]
	v_cmp_le_i32_e32 vcc, s22, v145
	s_and_saveexec_b64 s[60:61], vcc
	s_cbranch_execz .LBB0_109
	s_bitcmp1_b32 s22, 0
	s_cselect_b32 s18, 0x5000, 0
	v_or_b32_e32 v32, s18, v155
	v_add_u32_e32 v33, v32, v157
	v_add_u32_e32 v44, v32, v158
	v_add_u32_e32 v48, v32, v159
	v_add_u32_e32 v49, v32, v160
	ds_read_b128 v[36:39], v33
	ds_read_b128 v[32:35], v33 offset:4096
	ds_read_b128 v[40:43], v44
	ds_read_b128 v[120:123], v44 offset:4096
	ds_read_b128 v[44:47], v48
	ds_read_b128 v[116:119], v48 offset:4096
	ds_read_b128 v[80:83], v49
	ds_read_b128 v[108:111], v49 offset:4096
	s_waitcnt lgkmcnt(0)
	v_mfma_f32_32x32x16_bf16 v[48:63], v[36:39], v[76:79], 0
	v_or_b32_e32 v36, s18, v150
	v_add_u32_e32 v37, v36, v154
	v_add_u32_e32 v38, v36, v153
	v_add_u32_e32 v39, v36, v151
	v_add_u32_e32 v36, v36, v152
	ds_read_b128 v[112:115], v37 offset:8192
	ds_read_b128 v[100:103], v38 offset:8192
	v_mfma_f32_32x32x16_bf16 v[48:63], v[40:43], v[72:75], v[48:63]
	v_mfma_f32_32x32x16_bf16 v[48:63], v[44:47], v[68:71], v[48:63]
	v_mfma_f32_32x32x16_bf16 v[48:63], v[80:83], v[64:67], v[48:63]
	ds_read_b128 v[80:83], v39 offset:8192
	ds_read_b128 v[84:87], v36 offset:8192
	ds_read_b128 v[104:107], v37 offset:12288
	ds_read_b128 v[96:99], v38 offset:12288
	ds_read_b128 v[92:95], v39 offset:12288
	ds_read_b128 v[88:91], v36 offset:12288
	v_cmp_ge_i32_e64 s[44:45], s22, v148
	s_nop 4
	v_pk_fma_f32 v[36:37], v[62:63], s[34:35], v[128:129] op_sel_hi:[1,0,1] neg_lo:[0,0,1] neg_hi:[0,0,1]
	s_cmp_lg_u64 s[44:45], 0
	s_cbranch_scc1 .Lmixa_near_0
.Lmixa_back_0:
	v_exp_f32_e32 v62, v36
	v_lshrrev_b32_e32 v36, v147, v166
	v_exp_f32_e32 v63, v37
	v_lshlrev_b32_e32 v166, 8, v36
	v_add_co_u32 v166, vcc, v166, v166
	v_cndmask_b32 v63, 0, v63, vcc
	v_pk_fma_f32 v[36:37], v[60:61], s[34:35], v[128:129] op_sel_hi:[1,0,1] neg_lo:[0,0,1] neg_hi:[0,0,1]
	v_add_co_u32 v166, vcc, v166, v166
	v_cndmask_b32 v62, 0, v62, vcc
	s_cbranch_scc1 .Lmixa_near_1
.Lmixa_back_1:
	v_exp_f32_e32 v61, v37
	v_exp_f32_e32 v60, v36
	v_mfma_f32_32x32x16_bf16 v[32:47], v[32:35], v[76:79], 0
	v_add_co_u32 v166, vcc, v166, v166
	v_cndmask_b32 v61, 0, v61, vcc
	s_nop 0
	v_add_co_u32 v166, vcc, v166, v166
	v_cndmask_b32 v60, 0, v60, vcc
	v_fma_f32 v58, v58, s34, -v128
	v_fma_f32 v59, v59, s34, -v129
	s_cbranch_scc1 .Lmixa_near_2
.Lmixa_back_2:
	v_exp_f32_e32 v59, v59
	v_exp_f32_e32 v58, v58
	v_add_co_u32 v166, vcc, v166, v166
	v_cndmask_b32 v59, 0, v59, vcc
	v_pk_fma_f32 v[56:57], v[56:57], s[34:35], v[128:129] op_sel_hi:[1,0,1] neg_lo:[0,0,1] neg_hi:[0,0,1]
	v_add_co_u32 v166, vcc, v166, v166
	v_cndmask_b32 v58, 0, v58, vcc
	s_cbranch_scc1 .Lmixa_near_3
.Lmixa_back_3:
	v_mfma_f32_32x32x16_bf16 v[32:47], v[120:123], v[72:75], v[32:47]
	v_exp_f32_e32 v57, v57
	v_exp_f32_e32 v56, v56
	v_add_co_u32 v166, vcc, v166, v166
	v_cndmask_b32 v57, 0, v57, vcc
	s_nop 0
	v_add_co_u32 v166, vcc, v166, v166
	v_cndmask_b32 v56, 0, v56, vcc
	v_pk_fma_f32 v[54:55], v[54:55], s[34:35], v[128:129] op_sel_hi:[1,0,1] neg_lo:[0,0,1] neg_hi:[0,0,1]
	s_cbranch_scc1 .Lmixa_near_4
.Lmixa_back_4:
	v_exp_f32_e32 v55, v55
	v_lshlrev_b32_e32 v120, 8, v166
	v_exp_f32_e32 v54, v54
	v_add_co_u32 v120, vcc, v120, v120
	v_cndmask_b32 v55, 0, v55, vcc
	v_pk_fma_f32 v[52:53], v[52:53], s[34:35], v[128:129] op_sel_hi:[1,0,1] neg_lo:[0,0,1] neg_hi:[0,0,1]
	v_add_co_u32 v120, vcc, v120, v120
	v_cndmask_b32 v54, 0, v54, vcc
	s_cbranch_scc1 .Lmixa_near_5
.Lmixa_back_5:
	v_mfma_f32_32x32x16_bf16 v[32:47], v[116:119], v[68:71], v[32:47]
	v_exp_f32_e32 v53, v53
	v_exp_f32_e32 v52, v52
	v_add_co_u32 v120, vcc, v120, v120
	v_cndmask_b32 v53, 0, v53, vcc
	s_nop 0
	v_add_co_u32 v120, vcc, v120, v120
	v_cndmask_b32 v52, 0, v52, vcc
	v_pk_fma_f32 v[50:51], v[50:51], s[34:35], v[128:129] op_sel_hi:[1,0,1] neg_lo:[0,0,1] neg_hi:[0,0,1]
	s_cbranch_scc1 .Lmixa_near_6
.Lmixa_back_6:
	v_exp_f32_e32 v117, v51
	v_exp_f32_e32 v116, v50
	v_add_co_u32 v120, vcc, v120, v120
	v_cndmask_b32 v117, 0, v117, vcc
	v_pk_fma_f32 v[50:51], v[48:49], s[34:35], v[128:129] op_sel_hi:[1,0,1] neg_lo:[0,0,1] neg_hi:[0,0,1]
	v_add_co_u32 v120, vcc, v120, v120
	v_cndmask_b32 v116, 0, v116, vcc
	s_cbranch_scc1 .Lmixa_near_7
.Lmixa_back_7:
	v_mfma_f32_32x32x16_bf16 v[32:47], v[108:111], v[64:67], v[32:47]
	v_exp_f32_e32 v119, v51
	v_exp_f32_e32 v118, v50
	v_add_co_u32 v120, vcc, v120, v120
	v_cndmask_b32 v119, 0, v119, vcc
	v_cvt_pk_bf16_f32 v49, v116, v117
	v_cvt_pk_bf16_f32 v50, v52, v53
	v_cvt_pk_bf16_f32 v51, v54, v55
	v_add_co_u32 v120, vcc, v120, v120
	v_cndmask_b32 v118, 0, v118, vcc
	s_nop 0
	v_cvt_pk_bf16_f32 v48, v118, v119
	s_waitcnt lgkmcnt(0)
	s_nop 0
	v_mfma_f32_32x32x16_bf16 v[0:15], v[112:115], v[48:51], v[0:15]
	s_nop 1
	v_fma_f32 v46, v46, s34, -v128
	v_fma_f32 v47, v47, s34, -v129
	s_cbranch_scc1 .Lmixa_near_8
; template <int DQK, bool MIXA, bool PIPE>
; DI void attn_item(const Params& P, int layer, char* smem, int b, int h, int qt) {
;     ...
;       auto chunk = [&](int kb, int c) __attribute__((always_inline)) {
;         const int s2 = 1 - (c >> 2), e = 3 - (c & 3);
;         const int r0 = 8 * s2 + 2 * e;
;         if (MIXA && c == 4) mrot[kb] <<= 8;
;         f32x2 xv2 = {sacc[kb][r0], sacc[kb][r0 + 1]};
;         xv2 = xv2 * sl2v - mfixv;
;         if (MIXA) {
;           if (near) {
;             const int kl = 16 * (r0 >> 3) + 8 * H + (r0 & 7);
;             const int rel = kc * 64 + 32 * kb + kl - qpos;
;             xv2.x += biasT[rel + 192];
;             xv2.y += biasT[rel + 193];
;           }
;         }
;         f32x2 p2 = {__builtin_amdgcn_exp2f(xv2.x), __builtin_amdgcn_exp2f(xv2.y)};
;         if (MIXA) {
;           float px = p2.x, py = p2.y;
;           asm volatile("v_add_co_u32 %0, vcc, %0, %0\n\tv_cndmask_b32 %1, 0, %1, vcc" : "+v"(mrot[kb]), "+v"(py) : : "vcc");
;           asm volatile("v_add_co_u32 %0, vcc, %0, %0\n\tv_cndmask_b32 %1, 0, %1, vcc" : "+v"(mrot[kb]), "+v"(px) : : "vcc");
;           p2.x = px; p2.y = py;
;         }
;         ls2 += p2;
;         pkw[kb][s2][e] = pk2(p2.x, p2.y);
;       };
;       {
;         int c0 = 0;
; #pragma unroll
;         for (int s = 0; s < NS; ++s) {
;           sacc[1] = __builtin_amdgcn_mfma_f32_32x32x16_bf16(kf[1][s], qf[s], sacc[1], 0, 0, 0);
;           const int cend = (8 * (s + 1)) / NS;
; #pragma unroll
;           for (int c = 0; c < 8; ++c) if (c >= c0 && c < cend) chunk(0, c);
;           c0 = cend;
;           __builtin_amdgcn_sched_barrier(0);
;         }
;       }
;       bf16x8 pf0[2], pf1[2];
; #pragma unroll
;       for (int s2 = 0; s2 < 2; ++s2) { u32x4 t = {pkw[0][s2][0], pkw[0][s2][1], pkw[0][s2][2], pkw[0][s2][3]}; pf0[s2] = __builtin_bit_cast(bf16x8, t); }
; #pragma unroll
;       for (int j = 0; j < 4; ++j) {
;         const int s2 = j >> 1, d = j & 1;
;         o[d] = __builtin_amdgcn_mfma_f32_32x32x16_bf16(vf[d][0][s2], pf0[s2], o[d], 0, 0, 0);
;         chunk(1, 2 * j); chunk(1, 2 * j + 1);
;         __builtin_amdgcn_sched_barrier(0);
;       }
; #pragma unroll
;       for (int s2 = 0; s2 < 2; ++s2) { u32x4 t = {pkw[1][s2][0], pkw[1][s2][1], pkw[1][s2][2], pkw[1][s2][3]}; pf1[s2] = __builtin_bit_cast(bf16x8, t); }
; #pragma unroll
;       for (int j = 0; j < 4; ++j) {
.Lmixa_back_8:
	v_lshrrev_b32_e32 v108, v147, v164
	v_exp_f32_e32 v47, v47
	v_lshlrev_b32_e32 v108, 8, v108
	v_exp_f32_e32 v46, v46
	v_add_co_u32 v108, vcc, v108, v108
	v_cndmask_b32 v47, 0, v47, vcc
	v_pk_fma_f32 v[44:45], v[44:45], s[34:35], v[128:129] op_sel_hi:[1,0,1] neg_lo:[0,0,1] neg_hi:[0,0,1]
	v_add_co_u32 v108, vcc, v108, v108
	v_cndmask_b32 v46, 0, v46, vcc
	s_cbranch_scc1 .Lmixa_near_9
.Lmixa_back_9:
	v_exp_f32_e32 v45, v45
	v_exp_f32_e32 v44, v44
	v_add_co_u32 v108, vcc, v108, v108
	v_cndmask_b32 v45, 0, v45, vcc
	s_nop 0
	v_add_co_u32 v108, vcc, v108, v108
	v_cndmask_b32 v44, 0, v44, vcc
	v_mfma_f32_32x32x16_bf16 v[16:31], v[104:107], v[48:51], v[16:31]
	v_fma_f32 v42, v42, s34, -v128
	v_fma_f32 v43, v43, s34, -v129
	s_cbranch_scc1 .Lmixa_near_10
.Lmixa_back_10:
	v_exp_f32_e32 v49, v43
	v_exp_f32_e32 v48, v42
	v_add_co_u32 v108, vcc, v108, v108
	v_cndmask_b32 v49, 0, v49, vcc
	v_pk_fma_f32 v[42:43], v[40:41], s[34:35], v[128:129] op_sel_hi:[1,0,1] neg_lo:[0,0,1] neg_hi:[0,0,1]
	v_add_co_u32 v108, vcc, v108, v108
	v_cndmask_b32 v48, 0, v48, vcc
	s_cbranch_scc1 .Lmixa_near_11
.Lmixa_back_11:
	v_exp_f32_e32 v51, v43
	v_cvt_pk_bf16_f32 v40, v56, v57
	v_cvt_pk_bf16_f32 v41, v58, v59
	v_exp_f32_e32 v50, v42
	v_cvt_pk_bf16_f32 v42, v60, v61
	v_cvt_pk_bf16_f32 v43, v62, v63
	v_add_co_u32 v108, vcc, v108, v108
	v_cndmask_b32 v51, 0, v51, vcc
	s_nop 0
	v_add_co_u32 v108, vcc, v108, v108
	v_cndmask_b32 v50, 0, v50, vcc
	s_nop 0
	v_mfma_f32_32x32x16_bf16 v[0:15], v[100:103], v[40:43], v[0:15]
	v_fma_f32 v38, v38, s34, -v128
	v_fma_f32 v39, v39, s34, -v129
	s_cbranch_scc1 .Lmixa_near_12
.Lmixa_back_12:
	v_exp_f32_e32 v39, v39
	v_lshlrev_b32_e32 v100, 8, v108
	v_exp_f32_e32 v38, v38
	v_add_co_u32 v100, vcc, v100, v100
	v_cndmask_b32 v39, 0, v39, vcc
	v_pk_fma_f32 v[36:37], v[36:37], s[34:35], v[128:129] op_sel_hi:[1,0,1] neg_lo:[0,0,1] neg_hi:[0,0,1]
	v_add_co_u32 v100, vcc, v100, v100
	v_cndmask_b32 v38, 0, v38, vcc
	s_cbranch_scc1 .Lmixa_near_13
.Lmixa_back_13:
	v_exp_f32_e32 v37, v37
	v_exp_f32_e32 v36, v36
	v_add_co_u32 v100, vcc, v100, v100
	v_cndmask_b32 v37, 0, v37, vcc
	s_nop 0
	v_add_co_u32 v100, vcc, v100, v100
	v_cndmask_b32 v36, 0, v36, vcc
	v_mfma_f32_32x32x16_bf16 v[16:31], v[96:99], v[40:43], v[16:31]
	v_fma_f32 v34, v34, s34, -v128
	v_fma_f32 v35, v35, s34, -v129
	s_cbranch_scc1 .Lmixa_near_14
.Lmixa_back_14:
	v_exp_f32_e32 v35, v35
	v_exp_f32_e32 v34, v34
	v_add_co_u32 v100, vcc, v100, v100
	v_cndmask_b32 v35, 0, v35, vcc
	v_pk_fma_f32 v[32:33], v[32:33], s[34:35], v[128:129] op_sel_hi:[1,0,1] neg_lo:[0,0,1] neg_hi:[0,0,1]
	v_add_co_u32 v100, vcc, v100, v100
	v_cndmask_b32 v34, 0, v34, vcc
	s_cbranch_scc0 .LBB0_108
	ds_read2_b32 v[40:41], v162 offset0:32 offset1:33
	s_waitcnt lgkmcnt(0)
	v_pk_add_f32 v[32:33], v[32:33], v[40:41]
	s_branch .LBB0_108
.Lmixa_near_0:
	ds_read2_b32 v[38:39], v162 offset0:22 offset1:23
	s_waitcnt lgkmcnt(0)
	v_pk_add_f32 v[36:37], v[36:37], v[38:39]
	s_branch .Lmixa_back_0
.Lmixa_near_1:
	ds_read2_b32 v[38:39], v162 offset0:20 offset1:21
	s_waitcnt lgkmcnt(0)
	v_pk_add_f32 v[36:37], v[36:37], v[38:39]
	s_branch .Lmixa_back_1
.Lmixa_near_2:
	ds_read2_b32 v[208:209], v162 offset0:18 offset1:19
	s_waitcnt lgkmcnt(0)
	v_pk_add_f32 v[58:59], v[58:59], v[208:209]
	s_branch .Lmixa_back_2
.Lmixa_near_3:
	ds_read2_b32 v[208:209], v162 offset0:16 offset1:17
	s_waitcnt lgkmcnt(0)
	v_pk_add_f32 v[56:57], v[56:57], v[208:209]
	s_branch .Lmixa_back_3
.Lmixa_near_4:
	ds_read2_b32 v[120:121], v162 offset0:6 offset1:7
	s_waitcnt lgkmcnt(0)
	v_pk_add_f32 v[54:55], v[54:55], v[120:121]
	s_branch .Lmixa_back_4
.Lmixa_near_5:
	ds_read2_b32 v[122:123], v162 offset0:4 offset1:5
	s_waitcnt lgkmcnt(0)
	v_pk_add_f32 v[52:53], v[52:53], v[122:123]
	s_branch .Lmixa_back_5
.Lmixa_near_6:
	ds_read2_b32 v[116:117], v162 offset0:2 offset1:3
	s_waitcnt lgkmcnt(0)
	v_pk_add_f32 v[50:51], v[50:51], v[116:117]
	s_branch .Lmixa_back_6
.Lmixa_near_7:
	ds_read2_b32 v[48:49], v162 offset1:1
	s_waitcnt lgkmcnt(0)
	v_pk_add_f32 v[50:51], v[50:51], v[48:49]
	s_branch .Lmixa_back_7
.Lmixa_near_8:
	ds_read2_b32 v[108:109], v162 offset0:54 offset1:55
	s_waitcnt lgkmcnt(0)
	v_pk_add_f32 v[46:47], v[46:47], v[108:109]
	s_branch .Lmixa_back_8
.Lmixa_near_9:
	ds_read2_b32 v[110:111], v162 offset0:52 offset1:53
	s_waitcnt lgkmcnt(0)
	v_pk_add_f32 v[44:45], v[44:45], v[110:111]
	s_branch .Lmixa_back_9
.Lmixa_near_10:
	ds_read2_b32 v[48:49], v162 offset0:50 offset1:51
	s_waitcnt lgkmcnt(0)
	v_pk_add_f32 v[42:43], v[42:43], v[48:49]
	s_branch .Lmixa_back_10
.Lmixa_near_11:
	ds_read2_b32 v[40:41], v162 offset0:48 offset1:49
	s_waitcnt lgkmcnt(0)
	v_pk_add_f32 v[42:43], v[42:43], v[40:41]
	s_branch .Lmixa_back_11
.Lmixa_near_12:
	ds_read2_b32 v[100:101], v162 offset0:38 offset1:39
	s_waitcnt lgkmcnt(0)
	v_pk_add_f32 v[38:39], v[38:39], v[100:101]
	s_branch .Lmixa_back_12
.Lmixa_near_13:
	ds_read2_b32 v[102:103], v162 offset0:36 offset1:37
	s_waitcnt lgkmcnt(0)
	v_pk_add_f32 v[36:37], v[36:37], v[102:103]
	s_branch .Lmixa_back_13
.Lmixa_near_14:
	ds_read2_b32 v[40:41], v162 offset0:34 offset1:35
	s_waitcnt lgkmcnt(0)
	v_pk_add_f32 v[34:35], v[34:35], v[40:41]
	s_branch .Lmixa_back_14
